# v023: sample-sequence conv item: one unconditional load wait per staging stage, per-block and post-barrier waits that only covered carry stores removed
# baseline (speedup 1.0000x reference)
.LBB0_588:
	s_or_b64 exec, exec, s[12:13]
	s_add_u32 s6, s10, s8
	s_addc_u32 s7, s11, s9
	v_mov_b32_e32 v77, v193
	v_add_u32_e32 v95, 0, v76
	v_lshl_add_u64 v[36:37], s[6:7], 0, v[76:77]
	s_mov_b64 s[6:7], 0x6578000
	v_lshl_add_u64 v[36:37], v[36:37], 0, s[6:7]
	v_lshl_add_u32 v96, v78, 11, v95
	s_waitcnt vmcnt(0) lgkmcnt(0)
	s_and_saveexec_b64 s[6:7], vcc
	s_cbranch_execz .LBB0_591
	v_lshlrev_b32_e32 v38, 16, v4
	v_and_b32_e32 v39, 0xffff0000, v4
	v_lshlrev_b32_e32 v40, 16, v5
	v_and_b32_e32 v41, 0xffff0000, v5
	v_lshlrev_b32_e32 v4, 16, v6
	v_and_b32_e32 v5, 0xffff0000, v6
	v_lshlrev_b32_e32 v6, 16, v7
	v_and_b32_e32 v7, 0xffff0000, v7
	v_cmp_gt_i32_e32 vcc, 15, v78
	s_nop 1
	v_cndmask_b32_e32 v7, v7, v15, vcc
	v_cndmask_b32_e32 v6, v6, v14, vcc
	v_cndmask_b32_e32 v5, v5, v13, vcc
	v_cndmask_b32_e32 v4, v4, v12, vcc
	v_cndmask_b32_e32 v11, v41, v11, vcc
	v_cndmask_b32_e32 v10, v40, v10, vcc
	v_cndmask_b32_e32 v9, v39, v9, vcc
	v_cndmask_b32_e32 v8, v38, v8, vcc
	v_cmp_lt_i32_e32 vcc, 7, v78
	ds_write_b128 v96, v[8:11]
	ds_write_b128 v96, v[4:7] offset:16
	s_and_b64 exec, exec, vcc
	s_cbranch_execz .LBB0_591
	v_add_u32_e32 v12, -8, v78
	v_mov_b32_e32 v13, v193
	v_lshlrev_b64 v[12:13], 11, v[12:13]
	v_lshl_add_u64 v[12:13], v[36:37], 0, v[12:13]
	global_store_dwordx4 v[12:13], v[8:11], off
	global_store_dwordx4 v[12:13], v[4:7], off offset:16
.LBB0_591:
	s_or_b64 exec, exec, s[6:7]
	v_lshl_add_u32 v97, v80, 11, v95
	s_and_saveexec_b64 s[6:7], s[0:1]
	s_cbranch_execz .LBB0_594
	v_lshlrev_b32_e32 v4, 16, v24
	v_and_b32_e32 v5, 0xffff0000, v24
	v_lshlrev_b32_e32 v6, 16, v25
	v_and_b32_e32 v7, 0xffff0000, v25
	v_lshlrev_b32_e32 v8, 16, v26
	v_and_b32_e32 v9, 0xffff0000, v26
	v_lshlrev_b32_e32 v10, 16, v27
	v_and_b32_e32 v11, 0xffff0000, v27
	v_cmp_gt_i32_e32 vcc, 15, v80
	s_nop 1
	v_cndmask_b32_e32 v3, v11, v3, vcc
	v_cndmask_b32_e32 v2, v10, v2, vcc
	v_cndmask_b32_e32 v1, v9, v1, vcc
	v_cndmask_b32_e32 v0, v8, v0, vcc
	v_cndmask_b32_e32 v7, v7, v23, vcc
	v_cndmask_b32_e32 v6, v6, v22, vcc
	v_cndmask_b32_e32 v5, v5, v21, vcc
	v_cndmask_b32_e32 v4, v4, v20, vcc
	v_cmp_lt_i32_e32 vcc, 7, v80
	ds_write_b128 v97, v[4:7]
	ds_write_b128 v97, v[0:3] offset:16
	s_and_b64 exec, exec, vcc
	s_cbranch_execz .LBB0_594
	v_add_u32_e32 v8, -8, v80
	v_mov_b32_e32 v9, v193
	v_lshlrev_b64 v[8:9], 11, v[8:9]
	v_lshl_add_u64 v[8:9], v[36:37], 0, v[8:9]
	global_store_dwordx4 v[8:9], v[4:7], off
	global_store_dwordx4 v[8:9], v[0:3], off offset:16
.LBB0_594:
	s_or_b64 exec, exec, s[6:7]
	v_lshl_add_u32 v104, v82, 11, v95
	s_and_saveexec_b64 s[0:1], s[4:5]
	s_cbranch_execz .LBB0_597
	v_lshlrev_b32_e32 v4, 16, v28
	v_and_b32_e32 v5, 0xffff0000, v28
	v_lshlrev_b32_e32 v6, 16, v29
	v_and_b32_e32 v7, 0xffff0000, v29
	v_lshlrev_b32_e32 v0, 16, v30
	v_and_b32_e32 v1, 0xffff0000, v30
	v_lshlrev_b32_e32 v2, 16, v31
	v_and_b32_e32 v3, 0xffff0000, v31
	v_cmp_gt_i32_e32 vcc, 15, v82
	s_nop 1
	v_cndmask_b32_e32 v3, v3, v35, vcc
	v_cndmask_b32_e32 v2, v2, v34, vcc
	v_cndmask_b32_e32 v1, v1, v33, vcc
	v_cndmask_b32_e32 v0, v0, v32, vcc
	v_cndmask_b32_e32 v7, v7, v19, vcc
	v_cndmask_b32_e32 v6, v6, v18, vcc
	v_cndmask_b32_e32 v5, v5, v17, vcc
	v_cndmask_b32_e32 v4, v4, v16, vcc
	v_cmp_lt_i32_e32 vcc, 7, v82
	ds_write_b128 v104, v[4:7]
	ds_write_b128 v104, v[0:3] offset:16
	s_and_b64 exec, exec, vcc
	s_cbranch_execz .LBB0_597
	v_add_u32_e32 v8, -8, v82
	v_mov_b32_e32 v9, v193
	v_lshlrev_b64 v[8:9], 11, v[8:9]
	v_lshl_add_u64 v[8:9], v[36:37], 0, v[8:9]
	global_store_dwordx4 v[8:9], v[4:7], off
	global_store_dwordx4 v[8:9], v[0:3], off offset:16
.LBB0_597:
	s_or_b64 exec, exec, s[0:1]
	v_lshl_add_u32 v92, v64, 2, 0
	s_mov_b64 s[6:7], -1
	s_mov_b64 s[0:1], 0
	s_cmp_lt_i32 s2, 1
	s_mov_b64 s[4:5], 0
	s_waitcnt lgkmcnt(0)
	s_barrier
	s_cbranch_scc1 .LBB0_602
	s_cmp_gt_i32 s2, 1
	s_cbranch_scc0 .LBB0_713
	s_cmp_eq_u32 s2, 2
	s_mov_b64 s[4:5], -1
	s_cbranch_scc0 .LBB0_601
	ds_read2st64_b32 v[0:1], v92 offset0:64 offset1:72
	ds_read2st64_b32 v[2:3], v92 offset0:80 offset1:88
	ds_read2st64_b32 v[4:5], v92 offset0:96 offset1:104
	ds_read2st64_b32 v[6:7], v92 offset0:160 offset1:168
	ds_read_b32 v9, v92 offset:45056
	ds_read2st64_b32 v[10:11], v92 offset0:144 offset1:152
	ds_read2st64_b32 v[12:13], v92 offset0:112 offset1:120
	ds_read2st64_b32 v[14:15], v92 offset0:128 offset1:136
	s_waitcnt lgkmcnt(4)
	v_mov_b32_e32 v8, v7
	v_mov_b32_e32 v19, v6
	s_waitcnt lgkmcnt(2)
	v_mov_b32_e32 v18, v11
	v_mov_b32_e32 v23, v10
	s_waitcnt lgkmcnt(0)
	v_mov_b32_e32 v22, v15
	v_pk_add_f32 v[16:17], v[8:9], 0 op_sel_hi:[1,0]
	v_pk_add_f32 v[20:21], v[18:19], 0 op_sel_hi:[1,0]
	v_pk_add_f32 v[24:25], v[22:23], 0 op_sel_hi:[1,0]
	v_mov_b32_e32 v26, v13
	v_mov_b32_e32 v27, v14
	v_pk_add_f32 v[28:29], v[26:27], 0 op_sel_hi:[1,0]
	v_pk_add_f32 v[24:25], v[14:15], v[24:25]
	v_pk_add_f32 v[20:21], v[10:11], v[20:21]
	v_pk_add_f32 v[16:17], v[6:7], v[16:17]
	v_pk_add_f32 v[28:29], v[12:13], v[28:29]
	v_pk_add_f32 v[16:17], v[18:19], v[16:17]
	v_pk_add_f32 v[18:19], v[22:23], v[20:21]
	v_pk_add_f32 v[20:21], v[26:27], v[24:25]
	v_mov_b32_e32 v24, v5
	v_mov_b32_e32 v25, v12
	v_pk_add_f32 v[28:29], v[24:25], v[28:29]
	v_pk_add_f32 v[20:21], v[12:13], v[20:21]
	v_pk_add_f32 v[16:17], v[10:11], v[16:17]
	v_pk_add_f32 v[28:29], v[4:5], v[28:29]
	v_pk_add_f32 v[18:19], v[14:15], v[18:19]
	v_pk_add_f32 v[16:17], v[22:23], v[16:17]
	v_pk_add_f32 v[20:21], v[24:25], v[20:21]
	v_mov_b32_e32 v22, v3
	v_mov_b32_e32 v23, v4
	v_pk_add_f32 v[18:19], v[26:27], v[18:19]
	v_pk_add_f32 v[28:29], v[22:23], v[28:29]
	v_pk_add_f32 v[20:21], v[4:5], v[20:21]
	v_pk_add_f32 v[28:29], v[2:3], v[28:29]
	v_pk_add_f32 v[18:19], v[12:13], v[18:19]
	v_pk_add_f32 v[16:17], v[14:15], v[16:17]
	v_pk_add_f32 v[20:21], v[22:23], v[20:21]
	v_mov_b32_e32 v22, v1
	v_mov_b32_e32 v23, v2
	v_pk_add_f32 v[16:17], v[26:27], v[16:17]
	v_pk_add_f32 v[18:19], v[24:25], v[18:19]
	v_pk_add_f32 v[22:23], v[22:23], v[28:29]
	v_pk_add_f32 v[20:21], v[2:3], v[20:21]
	v_pk_add_f32 v[22:23], v[0:1], v[22:23]
	v_pk_add_f32 v[2:3], v[4:5], v[18:19]
	v_pk_add_f32 v[0:1], v[12:13], v[16:17]
	v_xor_b32_e32 v5, 0x80000000, v9
	v_xor_b32_e32 v4, 0x80000000, v7
	s_mov_b32 s4, 0x3e000000
	v_pk_fma_f32 v[0:1], v[0:1], s[4:5], v[4:5] op_sel_hi:[1,0,1]
	v_xor_b32_e32 v5, 0x80000000, v6
	v_xor_b32_e32 v4, 0x80000000, v11
	v_pk_fma_f32 v[2:3], v[2:3], s[4:5], v[4:5] op_sel_hi:[1,0,1]
	v_xor_b32_e32 v5, 0x80000000, v10
	v_xor_b32_e32 v4, 0x80000000, v15
	v_xor_b32_e32 v7, 0x80000000, v14
	v_xor_b32_e32 v6, 0x80000000, v13
	v_pk_fma_f32 v[4:5], v[20:21], s[4:5], v[4:5] op_sel_hi:[1,0,1]
	v_pk_fma_f32 v[6:7], v[22:23], s[4:5], v[6:7] op_sel_hi:[1,0,1]
	s_mov_b64 s[4:5], 0

.LBB0_605:
	ds_read2st64_b32 v[2:3], v92 offset0:160 offset1:168
	ds_read_b32 v1, v92 offset:45056
	ds_read2st64_b32 v[4:5], v92 offset0:144 offset1:152
	ds_read2st64_b32 v[6:7], v92 offset0:112 offset1:120
	ds_read2st64_b32 v[8:9], v92 offset0:128 offset1:136
	s_waitcnt lgkmcnt(4)
	v_mov_b32_e32 v0, v3
	v_mov_b32_e32 v13, v2
	s_waitcnt lgkmcnt(2)
	v_mov_b32_e32 v12, v5
	v_mov_b32_e32 v15, v4
	s_waitcnt lgkmcnt(0)
	v_mov_b32_e32 v14, v9
	v_mov_b32_e32 v16, v7
	v_mov_b32_e32 v17, v8
	v_pk_add_f32 v[10:11], v[0:1], 0 op_sel_hi:[1,0]
	v_pk_add_f32 v[12:13], v[12:13], 0 op_sel_hi:[1,0]
	v_pk_add_f32 v[14:15], v[14:15], 0 op_sel_hi:[1,0]
	v_pk_add_f32 v[16:17], v[16:17], 0 op_sel_hi:[1,0]
	v_pk_add_f32 v[14:15], v[8:9], v[14:15]
	v_pk_add_f32 v[16:17], v[6:7], v[16:17]
	v_pk_add_f32 v[12:13], v[4:5], v[12:13]
	v_pk_add_f32 v[10:11], v[2:3], v[10:11]
	v_xor_b32_e32 v1, 0x80000000, v1
	v_xor_b32_e32 v0, 0x80000000, v3
	v_xor_b32_e32 v3, 0x80000000, v2
	v_xor_b32_e32 v2, 0x80000000, v5
	v_xor_b32_e32 v5, 0x80000000, v4
	v_xor_b32_e32 v4, 0x80000000, v9
	v_xor_b32_e32 v9, 0x80000000, v8
	v_xor_b32_e32 v8, 0x80000000, v7
	v_pk_fma_f32 v[0:1], v[10:11], 0.5, v[0:1] op_sel_hi:[1,0,1]
	v_pk_fma_f32 v[2:3], v[12:13], 0.5, v[2:3] op_sel_hi:[1,0,1]
	v_pk_fma_f32 v[4:5], v[14:15], 0.5, v[4:5] op_sel_hi:[1,0,1]
	v_pk_fma_f32 v[6:7], v[16:17], 0.5, v[8:9] op_sel_hi:[1,0,1]
.LBB0_606:
	s_add_i32 s6, s26, 0x4000
	s_mov_b64 s[0:1], s[42:43]
	s_ashr_i32 s7, s6, 31
	s_lshl_b64 s[4:5], s[6:7], 12
	s_add_u32 s0, s0, s4
	s_addc_u32 s1, s1, s5
	v_lshl_add_u64 v[8:9], v[64:65], 1, s[0:1]
	v_cvt_pk_bf16_f32 v6, v6, s0
	s_brev_b32 s0, 40
	v_add_co_u32_e32 v10, vcc, s0, v8
	v_readlane_b32 s48, v250, 31
	s_nop 0
	v_addc_co_u32_e32 v11, vcc, 0, v9, vcc
	global_store_short v[10:11], v6, off
	v_cvt_pk_bf16_f32 v10, v7, s0
	s_mov_b32 s0, 0x14001000
	v_add_co_u32_e32 v6, vcc, s0, v8
	v_cvt_pk_bf16_f32 v4, v4, s0
	s_nop 0
	v_addc_co_u32_e32 v7, vcc, 0, v9, vcc
	s_mov_b32 s0, 0x14002000
	global_store_short v[6:7], v10, off
	v_add_co_u32_e32 v6, vcc, s0, v8
	v_readlane_b32 s54, v250, 37
	s_nop 0
	v_addc_co_u32_e32 v7, vcc, 0, v9, vcc
	global_store_short v[6:7], v4, off
	v_cvt_pk_bf16_f32 v6, v5, s0
	s_mov_b32 s0, 0x14003000
	v_add_co_u32_e32 v4, vcc, s0, v8
	v_cvt_pk_bf16_f32 v2, v2, s0
	s_nop 0
	v_addc_co_u32_e32 v5, vcc, 0, v9, vcc
	s_mov_b32 s0, 0x14004000
	global_store_short v[4:5], v6, off
	v_add_co_u32_e32 v4, vcc, s0, v8
	v_readlane_b32 s55, v250, 38
	s_nop 0
	v_addc_co_u32_e32 v5, vcc, 0, v9, vcc
	global_store_short v[4:5], v2, off
	v_cvt_pk_bf16_f32 v4, v3, s0
	s_mov_b32 s0, 0x14005000
	v_add_co_u32_e32 v2, vcc, s0, v8
	v_cvt_pk_bf16_f32 v0, v0, s0
	s_nop 0
	v_addc_co_u32_e32 v3, vcc, 0, v9, vcc
	s_mov_b32 s0, 0x14006000
	global_store_short v[2:3], v4, off
	v_add_co_u32_e32 v2, vcc, s0, v8
	v_mov_b32_e32 v77, v193
	s_nop 0
	v_addc_co_u32_e32 v3, vcc, 0, v9, vcc
	global_store_short v[2:3], v0, off
	v_cvt_pk_bf16_f32 v2, v1, s0
	s_mov_b32 s0, 0x14007000
	v_add_co_u32_e32 v0, vcc, s0, v8
	s_lshl_b64 s[0:1], s[16:17], 12
	s_add_u32 s0, s54, s0
	v_addc_co_u32_e32 v1, vcc, 0, v9, vcc
	s_addc_u32 s1, s55, s1
	global_store_short v[0:1], v2, off
	v_lshl_add_u64 v[0:1], s[18:19], 0, v[192:193]
	s_mov_b64 s[4:5], 0x18400400
	v_lshl_add_u64 v[24:25], s[0:1], 0, v[76:77]
	s_movk_i32 s0, 0x280
	s_mov_b64 s[8:9], s[40:41]
	s_add_i32 s3, s26, 0x3ffe
	v_lshl_add_u64 v[26:27], v[0:1], 0, s[4:5]
	v_cmp_gt_i32_e32 vcc, s0, v64
	v_mov_b32_e32 v4, 0
	v_mov_b32_e32 v0, 0
	v_mov_b32_e32 v12, 0
	v_mov_b32_e32 v13, 0
	v_mov_b32_e32 v14, 0
	v_mov_b32_e32 v15, 0
	v_mov_b32_e32 v8, 0
	v_mov_b32_e32 v9, 0
	v_mov_b32_e32 v10, 0
	v_mov_b32_e32 v11, 0
	v_mov_b32_e32 v5, 0
	v_mov_b32_e32 v6, 0
	v_mov_b32_e32 v7, 0
	s_waitcnt lgkmcnt(0)
	s_barrier
	v_readlane_b32 s49, v250, 32
	v_readlane_b32 s50, v250, 33
	v_readlane_b32 s51, v250, 34
	v_readlane_b32 s52, v250, 35
	v_readlane_b32 s53, v250, 36
	v_readlane_b32 s56, v250, 39
	v_readlane_b32 s57, v250, 40
	v_readlane_b32 s58, v250, 41
	v_readlane_b32 s59, v250, 42
	v_readlane_b32 s60, v250, 43
	v_readlane_b32 s61, v250, 44
	v_readlane_b32 s62, v250, 45
	v_readlane_b32 s63, v250, 46
	s_and_saveexec_b64 s[4:5], vcc
	s_cbranch_execz .LBB0_612
	v_cmp_lt_i32_e64 s[0:1], 1, v78
	s_and_saveexec_b64 s[10:11], s[0:1]
	s_xor_b64 s[0:1], exec, s[10:11]
	s_cbranch_execz .LBB0_609
	v_add_u32_e32 v1, s3, v78
	v_mad_i64_i32 v[2:3], s[10:11], v1, s76, v[26:27]
	global_load_dwordx4 v[4:7], v[2:3], off

.LBB0_618:
	s_or_b64 exec, exec, s[10:11]
	s_lshl_b64 s[4:5], s[16:17], 10
	s_lshl_b64 s[4:5], s[4:5], 2
	s_add_u32 s4, s8, s4
	s_addc_u32 s5, s9, s5
	v_mov_b32_e32 v77, v193
	v_lshl_add_u64 v[24:25], s[4:5], 0, v[76:77]
	s_mov_b64 s[4:5], 0x6cf8000
	v_lshl_add_u64 v[24:25], v[24:25], 0, s[4:5]
	s_waitcnt vmcnt(0) lgkmcnt(0)
	s_and_saveexec_b64 s[4:5], vcc
	s_cbranch_execz .LBB0_621
	v_lshlrev_b32_e32 v26, 16, v4
	v_and_b32_e32 v27, 0xffff0000, v4
	v_lshlrev_b32_e32 v28, 16, v5
	v_and_b32_e32 v29, 0xffff0000, v5
	v_lshlrev_b32_e32 v4, 16, v6
	v_and_b32_e32 v5, 0xffff0000, v6
	v_lshlrev_b32_e32 v6, 16, v7
	v_and_b32_e32 v7, 0xffff0000, v7
	v_cmp_gt_i32_e32 vcc, 2, v78
	s_nop 1
	v_cndmask_b32_e32 v7, v7, v15, vcc
	v_cndmask_b32_e32 v6, v6, v14, vcc
	v_cndmask_b32_e32 v5, v5, v13, vcc
	v_cndmask_b32_e32 v4, v4, v12, vcc
	v_cndmask_b32_e32 v11, v29, v11, vcc
	v_cndmask_b32_e32 v10, v28, v10, vcc
	v_cndmask_b32_e32 v9, v27, v9, vcc
	v_cndmask_b32_e32 v8, v26, v8, vcc
	v_cmp_lt_i32_e32 vcc, 7, v78
	ds_write_b128 v96, v[8:11]
	ds_write_b128 v96, v[4:7] offset:16
	s_and_b64 exec, exec, vcc
	s_cbranch_execz .LBB0_621
	v_add_u32_e32 v12, -8, v78
	v_mov_b32_e32 v13, v193
	v_lshlrev_b64 v[12:13], 11, v[12:13]
	v_lshl_add_u64 v[12:13], v[24:25], 0, v[12:13]
	global_store_dwordx4 v[12:13], v[8:11], off
	global_store_dwordx4 v[12:13], v[4:7], off offset:16
.LBB0_621:
	s_or_b64 exec, exec, s[4:5]
	s_and_saveexec_b64 s[4:5], s[0:1]
	s_cbranch_execz .LBB0_624
	v_lshlrev_b32_e32 v4, 16, v0
	v_and_b32_e32 v5, 0xffff0000, v0
	v_lshlrev_b32_e32 v6, 16, v1
	v_and_b32_e32 v7, 0xffff0000, v1
	v_lshlrev_b32_e32 v0, 16, v2
	v_and_b32_e32 v1, 0xffff0000, v2
	v_lshlrev_b32_e32 v2, 16, v3
	v_and_b32_e32 v3, 0xffff0000, v3
	v_cmp_gt_i32_e32 vcc, 2, v80
	s_nop 1
	v_cndmask_b32_e32 v3, v3, v23, vcc
	v_cndmask_b32_e32 v2, v2, v22, vcc
	v_cndmask_b32_e32 v1, v1, v21, vcc
	v_cndmask_b32_e32 v0, v0, v20, vcc
	v_cndmask_b32_e32 v7, v7, v19, vcc
	v_cndmask_b32_e32 v6, v6, v18, vcc
	v_cndmask_b32_e32 v5, v5, v17, vcc
	v_cndmask_b32_e32 v4, v4, v16, vcc
	v_cmp_lt_i32_e32 vcc, 7, v80
	ds_write_b128 v97, v[4:7]
	ds_write_b128 v97, v[0:3] offset:16
	s_and_b64 exec, exec, vcc
	s_cbranch_execz .LBB0_624
	v_add_u32_e32 v8, -8, v80
	v_mov_b32_e32 v9, v193
	v_lshlrev_b64 v[8:9], 11, v[8:9]
	v_lshl_add_u64 v[8:9], v[24:25], 0, v[8:9]
	global_store_dwordx4 v[8:9], v[4:7], off
	global_store_dwordx4 v[8:9], v[0:3], off offset:16
.LBB0_624:
	s_or_b64 exec, exec, s[4:5]
	s_movk_i32 s0, 0x200
	v_cmp_gt_i32_e32 vcc, s0, v64
	v_cmp_lt_i32_e64 s[0:1], -1, v78
	s_and_b64 s[20:21], vcc, s[0:1]
	v_mov_b32_e32 v0, 0
	v_add_u32_e32 v93, s6, v78
	v_mov_b32_e32 v1, 0
	v_mov_b32_e32 v2, 0
	v_mov_b32_e32 v3, 0
	s_and_saveexec_b64 s[0:1], s[20:21]
	s_cbranch_execz .LBB0_626
	v_mov_b64_e32 v[0:1], s[18:19]
	v_mad_i64_i32 v[0:1], s[4:5], v93, s76, v[0:1]
	v_lshl_add_u64 v[0:1], v[0:1], 0, v[192:193]
	v_add_co_u32_e32 v0, vcc, 0x18400000, v0
	s_nop 1
	v_addc_co_u32_e32 v1, vcc, 0, v1, vcc
	global_load_dwordx4 v[0:3], v[0:1], off offset:2048

.LBB0_658:
	s_or_b64 exec, exec, s[26:27]
	s_add_u32 s12, s24, s22
	s_addc_u32 s13, s25, s23
	v_mov_b32_e32 v77, v193
	v_lshl_add_u64 v[84:85], s[12:13], 0, v[76:77]
	s_mov_b64 s[12:13], 0x6df8000
	v_lshl_add_u64 v[84:85], v[84:85], 0, s[12:13]
	s_waitcnt vmcnt(0) lgkmcnt(0)
	s_and_saveexec_b64 s[12:13], vcc
	s_cbranch_execz .LBB0_661
	v_lshlrev_b32_e32 v77, 16, v4
	v_and_b32_e32 v79, 0xffff0000, v4
	v_lshlrev_b32_e32 v81, 16, v5
	v_and_b32_e32 v83, 0xffff0000, v5
	v_lshlrev_b32_e32 v4, 16, v6
	v_and_b32_e32 v5, 0xffff0000, v6
	v_lshlrev_b32_e32 v6, 16, v7
	v_and_b32_e32 v7, 0xffff0000, v7
	v_cmp_gt_i32_e32 vcc, 30, v78
	s_nop 1
	v_cndmask_b32_e32 v7, v7, v15, vcc
	v_cndmask_b32_e32 v6, v6, v14, vcc
	v_cndmask_b32_e32 v5, v5, v13, vcc
	v_cndmask_b32_e32 v4, v4, v12, vcc
	v_cndmask_b32_e32 v11, v83, v11, vcc
	v_cndmask_b32_e32 v10, v81, v10, vcc
	v_cndmask_b32_e32 v9, v79, v9, vcc
	v_cndmask_b32_e32 v8, v77, v8, vcc
	v_cmp_lt_i32_e32 vcc, 7, v78
	ds_write_b128 v96, v[8:11]
	ds_write_b128 v96, v[4:7] offset:16
	s_and_b64 exec, exec, vcc
	s_cbranch_execz .LBB0_661
	v_add_u32_e32 v12, -8, v78
	v_mov_b32_e32 v13, v193
	v_lshlrev_b64 v[12:13], 11, v[12:13]
	v_lshl_add_u64 v[12:13], v[84:85], 0, v[12:13]
	global_store_dwordx4 v[12:13], v[8:11], off
	global_store_dwordx4 v[12:13], v[4:7], off offset:16
.LBB0_661:
	s_or_b64 exec, exec, s[12:13]
	s_and_saveexec_b64 s[12:13], s[10:11]
	s_cbranch_execz .LBB0_664
	v_lshlrev_b32_e32 v8, 16, v16
	v_and_b32_e32 v9, 0xffff0000, v16
	v_lshlrev_b32_e32 v10, 16, v17
	v_and_b32_e32 v11, 0xffff0000, v17
	v_lshlrev_b32_e32 v4, 16, v18
	v_and_b32_e32 v5, 0xffff0000, v18
	v_lshlrev_b32_e32 v6, 16, v19
	v_and_b32_e32 v7, 0xffff0000, v19
	v_cmp_gt_i32_e32 vcc, 30, v80
	s_nop 1
	v_cndmask_b32_e32 v7, v7, v23, vcc
	v_cndmask_b32_e32 v6, v6, v22, vcc
	v_cndmask_b32_e32 v5, v5, v21, vcc
	v_cndmask_b32_e32 v4, v4, v20, vcc
	v_cndmask_b32_e32 v3, v11, v3, vcc
	v_cndmask_b32_e32 v2, v10, v2, vcc
	v_cndmask_b32_e32 v1, v9, v1, vcc
	v_cndmask_b32_e32 v0, v8, v0, vcc
	v_cmp_lt_i32_e32 vcc, 7, v80
	ds_write_b128 v97, v[0:3]
	ds_write_b128 v97, v[4:7] offset:16
	s_and_b64 exec, exec, vcc
	s_cbranch_execz .LBB0_664
	v_add_u32_e32 v8, -8, v80
	v_mov_b32_e32 v9, v193
	v_lshlrev_b64 v[8:9], 11, v[8:9]
	v_lshl_add_u64 v[8:9], v[84:85], 0, v[8:9]
	global_store_dwordx4 v[8:9], v[0:3], off
	global_store_dwordx4 v[8:9], v[4:7], off offset:16
.LBB0_664:
	s_or_b64 exec, exec, s[12:13]
	s_and_saveexec_b64 s[10:11], s[4:5]
	s_cbranch_execz .LBB0_667
	v_lshlrev_b32_e32 v4, 16, v28
	v_and_b32_e32 v5, 0xffff0000, v28
	v_lshlrev_b32_e32 v6, 16, v29
	v_and_b32_e32 v7, 0xffff0000, v29
	v_lshlrev_b32_e32 v0, 16, v30
	v_and_b32_e32 v1, 0xffff0000, v30
	v_lshlrev_b32_e32 v2, 16, v31
	v_and_b32_e32 v3, 0xffff0000, v31
	v_cmp_gt_i32_e32 vcc, 30, v82
	s_nop 1
	v_cndmask_b32_e32 v3, v3, v39, vcc
	v_cndmask_b32_e32 v2, v2, v38, vcc
	v_cndmask_b32_e32 v1, v1, v37, vcc
	v_cndmask_b32_e32 v0, v0, v36, vcc
	v_cndmask_b32_e32 v7, v7, v35, vcc
	v_cndmask_b32_e32 v6, v6, v34, vcc
	v_cndmask_b32_e32 v5, v5, v33, vcc
	v_cndmask_b32_e32 v4, v4, v32, vcc
	v_cmp_lt_i32_e32 vcc, 7, v82
	ds_write_b128 v104, v[4:7]
	ds_write_b128 v104, v[0:3] offset:16
	s_and_b64 exec, exec, vcc
	s_cbranch_execz .LBB0_667
	v_add_u32_e32 v8, -8, v82
	v_mov_b32_e32 v9, v193
	v_lshlrev_b64 v[8:9], 11, v[8:9]
	v_lshl_add_u64 v[8:9], v[84:85], 0, v[8:9]
	global_store_dwordx4 v[8:9], v[4:7], off
	global_store_dwordx4 v[8:9], v[0:3], off offset:16
.LBB0_667:
	s_or_b64 exec, exec, s[10:11]
	s_and_saveexec_b64 s[4:5], s[6:7]
	s_cbranch_execz .LBB0_670
	v_lshlrev_b32_e32 v4, 16, v40
	v_and_b32_e32 v5, 0xffff0000, v40
	v_lshlrev_b32_e32 v6, 16, v41
	v_and_b32_e32 v7, 0xffff0000, v41
	v_lshlrev_b32_e32 v0, 16, v42
	v_and_b32_e32 v1, 0xffff0000, v42
	v_lshlrev_b32_e32 v2, 16, v43
	v_and_b32_e32 v3, 0xffff0000, v43
	v_cmp_gt_i32_e32 vcc, 30, v88
	v_lshl_add_u32 v8, v88, 11, v95
	s_nop 0
	v_cndmask_b32_e32 v3, v3, v47, vcc
	v_cndmask_b32_e32 v2, v2, v46, vcc
	v_cndmask_b32_e32 v1, v1, v45, vcc
	v_cndmask_b32_e32 v0, v0, v44, vcc
	v_cndmask_b32_e32 v7, v7, v27, vcc
	v_cndmask_b32_e32 v6, v6, v26, vcc
	v_cndmask_b32_e32 v5, v5, v25, vcc
	v_cndmask_b32_e32 v4, v4, v24, vcc
	v_cmp_lt_i32_e32 vcc, 7, v88
	ds_write_b128 v8, v[4:7]
	ds_write_b128 v8, v[0:3] offset:16
	s_and_b64 exec, exec, vcc
	s_cbranch_execz .LBB0_670
	v_add_u32_e32 v8, -8, v88
	v_mov_b32_e32 v9, v193
	v_lshlrev_b64 v[8:9], 11, v[8:9]
	v_lshl_add_u64 v[8:9], v[84:85], 0, v[8:9]
	global_store_dwordx4 v[8:9], v[4:7], off
	global_store_dwordx4 v[8:9], v[0:3], off offset:16
.LBB0_670:
	s_or_b64 exec, exec, s[4:5]
	s_and_saveexec_b64 s[4:5], s[8:9]
	s_cbranch_execz .LBB0_673
	v_lshlrev_b32_e32 v4, 16, v48
	v_and_b32_e32 v5, 0xffff0000, v48
	v_lshlrev_b32_e32 v6, 16, v49
	v_and_b32_e32 v7, 0xffff0000, v49
	v_lshlrev_b32_e32 v0, 16, v50
	v_and_b32_e32 v1, 0xffff0000, v50
	v_lshlrev_b32_e32 v2, 16, v51
	v_and_b32_e32 v3, 0xffff0000, v51
	v_cmp_gt_i32_e32 vcc, 30, v90
	v_lshl_add_u32 v8, v90, 11, v95
	s_nop 0
	v_cndmask_b32_e32 v3, v3, v59, vcc
	v_cndmask_b32_e32 v2, v2, v58, vcc
	v_cndmask_b32_e32 v1, v1, v57, vcc
	v_cndmask_b32_e32 v0, v0, v56, vcc
	v_cndmask_b32_e32 v7, v7, v55, vcc
	v_cndmask_b32_e32 v6, v6, v54, vcc
	v_cndmask_b32_e32 v5, v5, v53, vcc
	v_cndmask_b32_e32 v4, v4, v52, vcc
	v_cmp_lt_i32_e32 vcc, 7, v90
	ds_write_b128 v8, v[4:7]
	ds_write_b128 v8, v[0:3] offset:16
	s_and_b64 exec, exec, vcc
	s_cbranch_execz .LBB0_673
	v_add_u32_e32 v8, -8, v90
	v_mov_b32_e32 v9, v193
	v_lshlrev_b64 v[8:9], 11, v[8:9]
	v_lshl_add_u64 v[8:9], v[84:85], 0, v[8:9]
	global_store_dwordx4 v[8:9], v[4:7], off
	global_store_dwordx4 v[8:9], v[0:3], off offset:16
.LBB0_673:
	s_or_b64 exec, exec, s[4:5]
	s_waitcnt lgkmcnt(0)
	s_barrier
	ds_read2st64_b32 v[30:31], v92 offset1:8
	ds_read2st64_b32 v[34:35], v92 offset0:16 offset1:24
	ds_read2st64_b32 v[20:21], v92 offset0:32 offset1:40
	ds_read2st64_b32 v[0:1], v92 offset0:48 offset1:56
	ds_read2st64_b32 v[2:3], v92 offset0:64 offset1:72
	s_waitcnt lgkmcnt(4)
	v_fma_f32 v18, v150, v30, v60
	v_fmac_f32_e32 v18, v149, v31
	s_waitcnt lgkmcnt(3)
	v_fmac_f32_e32 v18, v148, v34
	v_fmac_f32_e32 v18, v147, v35
	s_waitcnt lgkmcnt(2)
	v_fmac_f32_e32 v18, v145, v20
	v_fmac_f32_e32 v18, v61, v21
	ds_read2st64_b32 v[4:5], v92 offset0:80 offset1:88
	s_waitcnt lgkmcnt(2)
	v_fmac_f32_e32 v18, v146, v0
	v_fmac_f32_e32 v18, v144, v1
	ds_read2st64_b32 v[6:7], v92 offset0:96 offset1:104
	s_waitcnt lgkmcnt(2)
	v_fmac_f32_e32 v18, v158, v2
	v_fmac_f32_e32 v18, v157, v3
	ds_read2st64_b32 v[8:9], v92 offset0:112 offset1:120
	s_waitcnt lgkmcnt(2)
	v_fmac_f32_e32 v18, v156, v4
	v_fmac_f32_e32 v18, v155, v5
	ds_read2st64_b32 v[10:11], v92 offset0:128 offset1:136
	s_waitcnt lgkmcnt(2)
	v_fmac_f32_e32 v18, v153, v6
	ds_read2st64_b32 v[12:13], v92 offset0:144 offset1:152
	ds_read2st64_b32 v[14:15], v92 offset0:160 offset1:168
	v_fmac_f32_e32 v18, v151, v7
	s_waitcnt lgkmcnt(3)
	v_fmac_f32_e32 v18, v154, v8
	v_fmac_f32_e32 v18, v152, v9
	s_waitcnt lgkmcnt(2)
	v_fmac_f32_e32 v18, v161, v10
	v_fmac_f32_e32 v18, v160, v11
	s_waitcnt lgkmcnt(1)
	v_mov_b32_e32 v16, v13
	s_waitcnt lgkmcnt(0)
	v_mov_b32_e32 v17, v14
	v_fmac_f32_e32 v18, v159, v12
	v_pk_mul_f32 v[16:17], v[68:69], v[16:17]
	v_cmp_eq_u32_e64 s[4:5], 0, v162
	v_add_f32_e32 v16, v18, v16
	v_add_f32_e32 v22, v16, v17
	ds_read2st64_b32 v[16:17], v92 offset0:176 offset1:184
	v_mov_b32_e32 v18, v15
	s_and_b32 s3, s64, 0xffffffc0
	s_waitcnt lgkmcnt(0)
	v_mov_b32_e32 v19, v16
	v_pk_mul_f32 v[18:19], v[62:63], v[18:19]
	s_nop 0
	v_add_f32_e32 v18, v22, v18
	v_add_f32_e32 v24, v18, v19
	ds_read2st64_b32 v[18:19], v92 offset0:192 offset1:200
	v_mov_b32_e32 v22, v17
	s_waitcnt lgkmcnt(0)
	v_mov_b32_e32 v23, v18
	v_pk_mul_f32 v[22:23], v[66:67], v[22:23]
	s_nop 0
	v_add_f32_e32 v22, v24, v22
	v_add_f32_e32 v26, v22, v23
	ds_read2st64_b32 v[22:23], v92 offset0:208 offset1:216
	v_mov_b32_e32 v24, v19
	s_waitcnt lgkmcnt(0)
	v_mov_b32_e32 v25, v22
	v_pk_mul_f32 v[24:25], v[74:75], v[24:25]
	s_nop 0
	v_add_f32_e32 v24, v26, v24
	ds_read2st64_b32 v[26:27], v92 offset0:224 offset1:232
	v_add_f32_e32 v28, v24, v25
	v_mov_b32_e32 v24, v23
	s_waitcnt lgkmcnt(0)
	v_mov_b32_e32 v25, v26
	v_pk_mul_f32 v[24:25], v[72:73], v[24:25]
	s_nop 0
	v_add_f32_e32 v24, v28, v24
	ds_read2st64_b32 v[28:29], v92 offset0:240 offset1:248
	v_add_f32_e32 v30, v24, v25
	v_mov_b32_e32 v24, v27
	s_waitcnt lgkmcnt(0)
	v_mov_b32_e32 v25, v28
	v_pk_mul_f32 v[24:25], v[70:71], v[24:25]
	s_nop 0
	v_add_f32_e32 v24, v30, v24
	v_add_f32_e32 v24, v24, v25
	v_mul_f32_e32 v25, v24, v24
	ds_bpermute_b32 v32, v103, v24
	ds_bpermute_b32 v33, v103, v25
	v_add_u32_e32 v30, 0x10000, v92
	ds_read_b32 v44, v30
	v_add_u32_e32 v30, 0x10800, v92
	ds_read_b32 v45, v30
	s_waitcnt lgkmcnt(2)
	v_pk_add_f32 v[32:33], v[24:25], v[32:33]
	ds_bpermute_b32 v36, v102, v32
	ds_bpermute_b32 v37, v102, v33
	v_add_u32_e32 v30, 0x11000, v92
	ds_read_b32 v46, v30
	v_add_u32_e32 v30, 0x11800, v92
	ds_read_b32 v47, v30
	s_waitcnt lgkmcnt(2)
	v_pk_add_f32 v[32:33], v[32:33], v[36:37]
	ds_bpermute_b32 v36, v101, v32
	ds_bpermute_b32 v37, v101, v33
	v_add_u32_e32 v30, 0x12000, v92
	ds_read_b32 v48, v30
	v_add_u32_e32 v30, 0x12800, v92
	ds_read_b32 v49, v30
	s_waitcnt lgkmcnt(2)
	v_pk_add_f32 v[32:33], v[32:33], v[36:37]
	ds_bpermute_b32 v36, v100, v32
	ds_bpermute_b32 v37, v100, v33
	s_waitcnt lgkmcnt(0)
	v_pk_add_f32 v[32:33], v[32:33], v[36:37]
	ds_bpermute_b32 v36, v99, v32
	ds_bpermute_b32 v37, v99, v33
	s_waitcnt lgkmcnt(0)
	v_pk_add_f32 v[32:33], v[32:33], v[36:37]
	ds_bpermute_b32 v36, v98, v32
	ds_bpermute_b32 v37, v98, v33
	s_and_saveexec_b64 s[6:7], s[4:5]
	s_cbranch_execz .LBB0_675
	s_add_i32 s8, s3, 0
	s_add_i32 s8, s8, 0x22000
	s_waitcnt lgkmcnt(0)
	v_pk_add_f32 v[32:33], v[32:33], v[36:37]
	v_mov_b32_e32 v25, s8
	ds_write_b64 v25, v[32:33]

.LBB0_713:
	s_and_b64 vcc, exec, s[6:7]
	s_cbranch_vccz .LBB0_715
	ds_read2st64_b32 v[0:1], v92 offset0:96 offset1:104
	ds_read2st64_b32 v[2:3], v92 offset0:160 offset1:168
	ds_read_b32 v5, v92 offset:45056
	ds_read2st64_b32 v[6:7], v92 offset0:144 offset1:152
	ds_read2st64_b32 v[8:9], v92 offset0:112 offset1:120
	ds_read2st64_b32 v[10:11], v92 offset0:128 offset1:136
	s_waitcnt lgkmcnt(4)
	v_mov_b32_e32 v4, v3
	v_mov_b32_e32 v15, v2
	s_waitcnt lgkmcnt(2)
	v_mov_b32_e32 v14, v7
	v_pk_add_f32 v[12:13], v[4:5], 0 op_sel_hi:[1,0]
	v_pk_add_f32 v[16:17], v[14:15], 0 op_sel_hi:[1,0]
	s_waitcnt lgkmcnt(1)
	v_mov_b32_e32 v22, v9
	s_waitcnt lgkmcnt(0)
	v_mov_b32_e32 v23, v10
	v_mov_b32_e32 v18, v11
	v_mov_b32_e32 v19, v6
	v_pk_add_f32 v[24:25], v[22:23], 0 op_sel_hi:[1,0]
	v_pk_add_f32 v[16:17], v[6:7], v[16:17]
	v_pk_add_f32 v[12:13], v[2:3], v[12:13]
	v_pk_add_f32 v[20:21], v[18:19], 0 op_sel_hi:[1,0]
	v_pk_add_f32 v[24:25], v[8:9], v[24:25]
	v_pk_add_f32 v[12:13], v[14:15], v[12:13]
	v_pk_add_f32 v[14:15], v[18:19], v[16:17]
	v_mov_b32_e32 v18, v1
	v_mov_b32_e32 v19, v8
	v_pk_add_f32 v[20:21], v[10:11], v[20:21]
	v_pk_add_f32 v[18:19], v[18:19], v[24:25]
	v_pk_add_f32 v[16:17], v[22:23], v[20:21]
	v_pk_add_f32 v[18:19], v[0:1], v[18:19]
	v_pk_add_f32 v[0:1], v[6:7], v[12:13]
	v_xor_b32_e32 v5, 0x80000000, v5
	v_xor_b32_e32 v4, 0x80000000, v3
	s_mov_b32 s6, 0x3e800000
	v_pk_add_f32 v[16:17], v[8:9], v[16:17]
	v_pk_add_f32 v[14:15], v[10:11], v[14:15]
	v_pk_fma_f32 v[0:1], v[0:1], s[6:7], v[4:5] op_sel_hi:[1,0,1]
	v_xor_b32_e32 v3, 0x80000000, v2
	v_xor_b32_e32 v2, 0x80000000, v7
	v_xor_b32_e32 v5, 0x80000000, v6
	v_xor_b32_e32 v4, 0x80000000, v11
	v_xor_b32_e32 v7, 0x80000000, v10
	v_xor_b32_e32 v6, 0x80000000, v9
	v_pk_fma_f32 v[2:3], v[14:15], s[6:7], v[2:3] op_sel_hi:[1,0,1]
	v_pk_fma_f32 v[4:5], v[16:17], s[6:7], v[4:5] op_sel_hi:[1,0,1]
	v_pk_fma_f32 v[6:7], v[18:19], s[6:7], v[6:7] op_sel_hi:[1,0,1]

.LBB0_717:
	ds_read2st64_b32 v[0:1], v92 offset1:8
	ds_read2st64_b32 v[2:3], v92 offset0:16 offset1:24
	ds_read2st64_b32 v[8:9], v92 offset0:32 offset1:40
	ds_read2st64_b32 v[10:11], v92 offset0:48 offset1:56
	ds_read2st64_b32 v[12:13], v92 offset0:64 offset1:72
	ds_read2st64_b32 v[14:15], v92 offset0:80 offset1:88
	ds_read2st64_b32 v[16:17], v92 offset0:96 offset1:104
	ds_read2st64_b32 v[18:19], v92 offset0:112 offset1:120
	ds_read2st64_b32 v[20:21], v92 offset0:128 offset1:136
	ds_read2st64_b32 v[22:23], v92 offset0:144 offset1:152
	ds_read2st64_b32 v[24:25], v92 offset0:160 offset1:168
	ds_read_b32 v27, v92 offset:45056
	s_waitcnt lgkmcnt(4)
	v_mov_b32_e32 v28, v19
	s_waitcnt lgkmcnt(3)
	v_mov_b32_e32 v29, v20
	v_pk_add_f32 v[4:5], v[28:29], 0 op_sel_hi:[1,0]
	v_mov_b32_e32 v30, v17
	v_pk_add_f32 v[4:5], v[18:19], v[4:5]
	v_mov_b32_e32 v31, v18
	v_pk_add_f32 v[4:5], v[30:31], v[4:5]
	v_mov_b32_e32 v32, v15
	v_pk_add_f32 v[4:5], v[16:17], v[4:5]
	v_mov_b32_e32 v33, v16
	v_pk_add_f32 v[4:5], v[32:33], v[4:5]
	v_mov_b32_e32 v34, v13
	v_pk_add_f32 v[4:5], v[14:15], v[4:5]
	v_mov_b32_e32 v35, v14
	v_pk_add_f32 v[4:5], v[34:35], v[4:5]
	v_mov_b32_e32 v36, v11
	v_pk_add_f32 v[4:5], v[12:13], v[4:5]
	v_mov_b32_e32 v37, v12
	v_pk_add_f32 v[4:5], v[36:37], v[4:5]
	v_mov_b32_e32 v38, v9
	v_pk_add_f32 v[4:5], v[10:11], v[4:5]
	v_mov_b32_e32 v39, v10
	v_pk_add_f32 v[4:5], v[38:39], v[4:5]
	v_mov_b32_e32 v40, v3
	v_pk_add_f32 v[4:5], v[8:9], v[4:5]
	v_mov_b32_e32 v41, v8
	v_pk_add_f32 v[4:5], v[40:41], v[4:5]
	v_mov_b32_e32 v6, v1
	v_pk_add_f32 v[4:5], v[2:3], v[4:5]
	v_mov_b32_e32 v7, v2
	v_pk_add_f32 v[4:5], v[6:7], v[4:5]
	s_mov_b32 s0, 0x3d800000
	v_pk_add_f32 v[0:1], v[0:1], v[4:5]
	s_waitcnt lgkmcnt(1)
	v_mov_b32_e32 v26, v25
	v_pk_fma_f32 v[6:7], v[0:1], s[0:1], v[28:29] op_sel_hi:[1,0,1] neg_lo:[0,0,1] neg_hi:[0,0,1]
	v_mov_b32_e32 v0, v21
	v_mov_b32_e32 v1, v22
	v_pk_add_f32 v[4:5], v[0:1], 0 op_sel_hi:[1,0]
	s_nop 0
	v_pk_add_f32 v[4:5], v[20:21], v[4:5]
	s_nop 0
	v_pk_add_f32 v[4:5], v[28:29], v[4:5]
	s_nop 0
	v_pk_add_f32 v[4:5], v[18:19], v[4:5]
	s_nop 0
	v_pk_add_f32 v[4:5], v[30:31], v[4:5]
	s_nop 0
	v_pk_add_f32 v[4:5], v[16:17], v[4:5]
	s_nop 0
	v_pk_add_f32 v[4:5], v[32:33], v[4:5]
	s_nop 0
	v_pk_add_f32 v[4:5], v[14:15], v[4:5]
	s_nop 0
	v_pk_add_f32 v[4:5], v[34:35], v[4:5]
	s_nop 0
	v_pk_add_f32 v[4:5], v[12:13], v[4:5]
	s_nop 0
	v_pk_add_f32 v[4:5], v[36:37], v[4:5]
	s_nop 0
	v_pk_add_f32 v[4:5], v[10:11], v[4:5]
	s_nop 0
	v_pk_add_f32 v[4:5], v[38:39], v[4:5]
	s_nop 0
	v_pk_add_f32 v[4:5], v[8:9], v[4:5]
	s_nop 0
	v_pk_add_f32 v[4:5], v[40:41], v[4:5]
	v_mov_b32_e32 v40, v23
	v_pk_add_f32 v[2:3], v[2:3], v[4:5]
	v_mov_b32_e32 v41, v24
	v_pk_fma_f32 v[4:5], v[2:3], s[0:1], v[0:1] op_sel_hi:[1,0,1] neg_lo:[0,0,1] neg_hi:[0,0,1]
	v_pk_add_f32 v[2:3], v[40:41], 0 op_sel_hi:[1,0]
	s_nop 0
	v_pk_add_f32 v[2:3], v[22:23], v[2:3]
	s_nop 0
	v_pk_add_f32 v[2:3], v[0:1], v[2:3]
	s_nop 0
	v_pk_add_f32 v[2:3], v[20:21], v[2:3]
	s_nop 0
	v_pk_add_f32 v[2:3], v[28:29], v[2:3]
	s_nop 0
	v_pk_add_f32 v[2:3], v[18:19], v[2:3]
	s_nop 0
	v_pk_add_f32 v[2:3], v[30:31], v[2:3]
	s_nop 0
	v_pk_add_f32 v[2:3], v[16:17], v[2:3]
	s_nop 0
	v_pk_add_f32 v[2:3], v[32:33], v[2:3]
	s_nop 0
	v_pk_add_f32 v[2:3], v[14:15], v[2:3]
	s_nop 0
	v_pk_add_f32 v[2:3], v[34:35], v[2:3]
	s_nop 0
	v_pk_add_f32 v[2:3], v[12:13], v[2:3]
	s_nop 0
	v_pk_add_f32 v[2:3], v[36:37], v[2:3]
	s_nop 0
	v_pk_add_f32 v[2:3], v[10:11], v[2:3]
	s_nop 0
	v_pk_add_f32 v[2:3], v[38:39], v[2:3]
	s_nop 0
	v_pk_add_f32 v[2:3], v[8:9], v[2:3]
	s_waitcnt lgkmcnt(0)
	v_pk_add_f32 v[8:9], v[26:27], 0 op_sel_hi:[1,0]
	v_pk_fma_f32 v[2:3], v[2:3], s[0:1], v[40:41] op_sel_hi:[1,0,1] neg_lo:[0,0,1] neg_hi:[0,0,1]
	v_pk_add_f32 v[8:9], v[24:25], v[8:9]
	s_nop 0
	v_pk_add_f32 v[8:9], v[40:41], v[8:9]
	s_nop 0
	v_pk_add_f32 v[8:9], v[22:23], v[8:9]
	s_nop 0
	v_pk_add_f32 v[0:1], v[0:1], v[8:9]
	s_nop 0
	v_pk_add_f32 v[0:1], v[20:21], v[0:1]
	s_nop 0
	v_pk_add_f32 v[0:1], v[28:29], v[0:1]
	s_nop 0
	v_pk_add_f32 v[0:1], v[18:19], v[0:1]
	s_nop 0
	v_pk_add_f32 v[0:1], v[30:31], v[0:1]
	s_nop 0
	v_pk_add_f32 v[0:1], v[16:17], v[0:1]
	s_nop 0
	v_pk_add_f32 v[0:1], v[32:33], v[0:1]
	s_nop 0
	v_pk_add_f32 v[0:1], v[14:15], v[0:1]
	s_nop 0
	v_pk_add_f32 v[0:1], v[34:35], v[0:1]
	s_nop 0
	v_pk_add_f32 v[0:1], v[12:13], v[0:1]
	s_nop 0
	v_pk_add_f32 v[0:1], v[36:37], v[0:1]
	s_nop 0
	v_pk_add_f32 v[0:1], v[10:11], v[0:1]
	s_nop 0
	v_pk_fma_f32 v[0:1], v[0:1], s[0:1], v[26:27] op_sel_hi:[1,0,1] neg_lo:[0,0,1] neg_hi:[0,0,1]
	s_cbranch_execz .LBB0_605
	s_branch .LBB0_606
